# all GEMM k-loops on v_mfma_f32_16x16x32_bf16; 256x128 loops use a bank-conflict-free LDS chunk swizzle f=[0,2,3,1] for the 16x16 fragment reads
# speedup vs baseline: 1.0020x; 1.0020x over previous
.LBB0_59:
	s_and_b32 s2, s2, 7
	v_readlane_b32 s4, v251, 7
	s_or_b32 s11, s2, s4
	s_lshl_b32 s10, s16, 7
	s_mul_i32 s2, s11, 0x160000
	s_add_u32 s4, s18, s2
	v_readlane_b32 s72, v250, 53
	s_addc_u32 s5, s19, 0
	s_mul_i32 s2, s16, 0xb0000
	v_readlane_b32 s84, v249, 1
	v_mov_b32_e32 v56, v200
	s_add_u32 s6, s84, s2
	s_movk_i32 s2, 0xb00
	v_ashrrev_i32_e32 v57, 2, v56
	v_lshlrev_b32_e32 v0, 3, v56
	s_waitcnt vmcnt(0)
	v_and_b32_e32 v188, 24, v0
	v_mad_i64_i32 v[0:1], s[8:9], v57, s2, 0
	v_lshlrev_b64 v[178:179], 1, v[0:1]
	v_add_u32_e32 v0, 64, v57
	v_mad_i64_i32 v[0:1], s[8:9], v0, s2, 0
	s_mul_hi_u32 s7, s10, 0x1600
	v_readlane_b32 s85, v249, 2
	v_lshlrev_b64 v[180:181], 1, v[0:1]
	v_add_u32_e32 v0, 0x80, v57
	s_addc_u32 s7, s85, s7
	v_lshlrev_b32_e32 v196, 1, v188
	v_mad_i64_i32 v[44:45], s[8:9], v0, s2, 0
	v_add_u32_e32 v0, 0xc0, v57
	v_lshl_add_u64 v[176:177], s[4:5], 0, v[196:197]
	v_mad_i64_i32 v[48:49], s[8:9], v0, s2, 0
	v_lshl_add_u64 v[182:183], s[6:7], 0, v[196:197]
	v_lshl_add_u64 v[40:41], v[176:177], 0, v[178:179]
	v_lshl_add_u64 v[42:43], v[176:177], 0, v[180:181]
	v_lshl_add_u64 v[46:47], v[44:45], 1, v[176:177]
	v_lshl_add_u64 v[50:51], v[48:49], 1, v[176:177]
	v_lshl_add_u64 v[52:53], v[182:183], 0, v[178:179]
	v_lshl_add_u64 v[54:55], v[182:183], 0, v[180:181]
	v_and_b32_e32 v192, 63, v200
	v_readfirstlane_b32 s44, v200
	v_lshrrev_b32_e32 v193, 2, v192
	v_and_b32_e32 v194, 3, v192
	v_lshrrev_b32_e32 v201, 4, v192
	s_lshr_b32 s44, s44, 6
	v_lshrrev_b32_e32 v212, 1, v201
	v_lshl_or_b32 v212, v212, 1, v212
	v_lshlrev_b32_e32 v201, 1, v201
	v_and_b32_e32 v201, 3, v201
	v_xor_b32_e32 v201, v201, v212
	v_xor_b32_e32 v206, v194, v201
	v_lshlrev_b32_e32 v206, 4, v206
	s_lshl_b32 s32, s44, 6
	v_add_u32_e32 v212, s32, v193
	v_mul_u32_u24_e32 v212, 0x1600, v212
	v_add_u32_e32 v234, v212, v206
	v_add_u32_e32 v235, 0x16000, v234
	v_add_u32_e32 v236, 0x2c000, v234
	v_add_u32_e32 v237, 0x42000, v234
	s_lshl_b32 s32, s44, 5
	v_add_u32_e32 v212, s32, v193
	v_mul_u32_u24_e32 v212, 0x1600, v212
	v_add_u32_e32 v238, v212, v206
	v_add_u32_e32 v239, 0x16000, v238
	v_and_b32_e32 v193, 15, v192
	v_lshrrev_b32_e32 v194, 4, v192
	v_bfe_u32 v201, v192, 2, 2
	v_lshrrev_b32_e32 v212, 1, v201
	v_lshl_or_b32 v212, v212, 1, v212
	v_lshlrev_b32_e32 v201, 1, v201
	v_and_b32_e32 v201, 3, v201
	v_xor_b32_e32 v201, v201, v212
	v_xor_b32_e32 v206, v194, v201
	v_lshlrev_b32_e32 v206, 4, v206
	v_lshl_add_u32 v206, v193, 6, v206
	s_lshr_b32 s32, s44, 1
	s_lshl_b32 s32, s32, 13
	v_add_u32_e32 v240, s32, v206
	v_xor_b32_e32 v241, 32, v240
	s_and_b32 s32, s44, 1
	s_lshl_b32 s32, s32, 12
	s_add_u32 s32, s32, 0x4000
	v_add_u32_e32 v242, s32, v206
	v_xor_b32_e32 v243, 32, v242
	s_lshl_b32 s46, s44, 12
	s_lshl_b32 s47, s44, 11
	s_add_u32 s47, s47, 0x4000
	s_mov_b32 s40, s4
	s_mov_b32 s41, s5
	s_mov_b32 s42, s6
	s_mov_b32 s43, s7
	s_add_u32 m0, s46, 0x0
	s_nop 0
	global_load_lds_dwordx4 v234, s[40:41]
	s_add_u32 m0, m0, 0x400
	s_nop 0
	global_load_lds_dwordx4 v235, s[40:41]
	s_add_u32 m0, m0, 0x400
	s_nop 0
	global_load_lds_dwordx4 v236, s[40:41]
	s_add_u32 m0, m0, 0x400
	s_nop 0
	global_load_lds_dwordx4 v237, s[40:41]
	s_add_u32 m0, s47, 0x0
	s_nop 0
	global_load_lds_dwordx4 v238, s[42:43]
	s_add_u32 m0, m0, 0x400
	s_nop 0
	global_load_lds_dwordx4 v239, s[42:43]
	s_add_u32 s40, s40, 64
	s_addc_u32 s41, s41, 0
	s_add_u32 s42, s42, 64
	s_addc_u32 s43, s43, 0
	s_add_u32 m0, s46, 0x6000
	s_nop 0
	global_load_lds_dwordx4 v234, s[40:41]
	s_add_u32 m0, m0, 0x400
	s_nop 0
	global_load_lds_dwordx4 v235, s[40:41]
	s_add_u32 m0, m0, 0x400
	s_nop 0
	global_load_lds_dwordx4 v236, s[40:41]
	s_add_u32 m0, m0, 0x400
	s_nop 0
	global_load_lds_dwordx4 v237, s[40:41]
	s_add_u32 m0, s47, 0x6000
	s_nop 0
	global_load_lds_dwordx4 v238, s[42:43]
	s_add_u32 m0, m0, 0x400
	s_nop 0
	global_load_lds_dwordx4 v239, s[42:43]
	s_add_u32 s40, s40, 64
	s_addc_u32 s41, s41, 0
	s_add_u32 s42, s42, 64
	s_addc_u32 s43, s43, 0
	s_mov_b32 s45, 0xc000
	s_mov_b32 s49, 0
	v_and_b32_e32 v58, 0xfffff9f, v56
	v_lshrrev_b32_e32 v59, 1, v56
	v_and_b32_e32 v56, 0x5f, v56
	s_movk_i32 s2, 0x50
	v_and_b32_e32 v59, 16, v59
	v_mad_u32_u24 v56, v56, s2, 0
	v_mul_lo_u32 v57, v57, s2
	v_mul_lo_u32 v58, v58, s2
	v_add_u32_e32 v189, v56, v59
	v_add_u32_e32 v56, 0, v196
	v_mov_b32_e32 v0, 0
	v_add_u32_e32 v58, 0, v58
	v_add_u32_e32 v191, v56, v57
	s_mov_b32 s17, 64
	s_mov_b32 s18, 0
	v_mov_b32_e32 v1, v0
	v_mov_b32_e32 v2, v0
	v_mov_b32_e32 v3, v0
	v_mov_b32_e32 v4, v0
	v_mov_b32_e32 v5, v0
	v_mov_b32_e32 v6, v0
	v_mov_b32_e32 v7, v0
	v_mov_b32_e32 v8, v0
	v_mov_b32_e32 v9, v0
	v_mov_b32_e32 v10, v0
	v_mov_b32_e32 v11, v0
	v_mov_b32_e32 v12, v0
	v_mov_b32_e32 v13, v0
	v_mov_b32_e32 v14, v0
	v_mov_b32_e32 v15, v0
	v_lshlrev_b64 v[184:185], 1, v[44:45]
	v_lshlrev_b64 v[186:187], 1, v[48:49]
	v_add_u32_e32 v190, v58, v59
	v_mov_b32_e32 v40, v0
	v_mov_b32_e32 v41, v0
	v_mov_b32_e32 v42, v0
	v_mov_b32_e32 v43, v0
	v_mov_b32_e32 v44, v0
	v_mov_b32_e32 v45, v0
	v_mov_b32_e32 v46, v0
	v_mov_b32_e32 v47, v0
	v_mov_b32_e32 v16, v0
	v_mov_b32_e32 v17, v0
	v_mov_b32_e32 v18, v0
	v_mov_b32_e32 v19, v0
	v_mov_b32_e32 v20, v0
	v_mov_b32_e32 v21, v0
	v_mov_b32_e32 v22, v0
	v_mov_b32_e32 v23, v0
	v_mov_b32_e32 v24, v0
	v_mov_b32_e32 v25, v0
	v_mov_b32_e32 v26, v0
	v_mov_b32_e32 v27, v0
	v_mov_b32_e32 v28, v0
	v_mov_b32_e32 v29, v0
	v_mov_b32_e32 v30, v0
	v_mov_b32_e32 v31, v0
	v_mov_b32_e32 v32, v0
	v_mov_b32_e32 v33, v0
	v_mov_b32_e32 v34, v0
	v_mov_b32_e32 v35, v0
	v_mov_b32_e32 v36, v0
	v_mov_b32_e32 v37, v0
	v_mov_b32_e32 v38, v0
	v_mov_b32_e32 v39, v0
	v_mov_b32_e32 v48, v0
	v_mov_b32_e32 v49, v0
	v_mov_b32_e32 v50, v0
	v_mov_b32_e32 v51, v0
	v_mov_b32_e32 v52, v0
	v_mov_b32_e32 v53, v0
	v_mov_b32_e32 v54, v0
	v_mov_b32_e32 v55, v0
	v_mov_b32_e32 v56, v0
	v_mov_b32_e32 v57, v0
	v_mov_b32_e32 v58, v0
	v_mov_b32_e32 v59, v0
	v_mov_b32_e32 v60, v0
	v_mov_b32_e32 v61, v0
	v_mov_b32_e32 v62, v0
	v_mov_b32_e32 v63, v0
	v_mov_b32_e32 v64, v0
	v_mov_b32_e32 v65, v0
	v_mov_b32_e32 v66, v0
	v_mov_b32_e32 v67, v0
	v_mov_b32_e32 v68, v0
	v_mov_b32_e32 v69, v0
	v_mov_b32_e32 v70, v0
	v_mov_b32_e32 v71, v0
	v_mov_b32_e32 v72, v0
	v_mov_b32_e32 v73, v0
	v_mov_b32_e32 v74, v0
	v_mov_b32_e32 v75, v0
	v_mov_b32_e32 v76, v0
	v_mov_b32_e32 v77, v0
	v_mov_b32_e32 v78, v0
	v_mov_b32_e32 v79, v0
	v_mov_b32_e32 v80, v0
	v_mov_b32_e32 v81, v0
	v_mov_b32_e32 v82, v0
	v_mov_b32_e32 v83, v0
	v_mov_b32_e32 v84, v0
	v_mov_b32_e32 v85, v0
	v_mov_b32_e32 v86, v0
	v_mov_b32_e32 v87, v0
	v_mov_b32_e32 v88, v0
	v_mov_b32_e32 v89, v0
	v_mov_b32_e32 v90, v0
	v_mov_b32_e32 v91, v0
	v_mov_b32_e32 v92, v0
	v_mov_b32_e32 v93, v0
	v_mov_b32_e32 v94, v0
	v_mov_b32_e32 v95, v0
	v_mov_b32_e32 v96, v0
	v_mov_b32_e32 v97, v0
	v_mov_b32_e32 v98, v0
	v_mov_b32_e32 v99, v0
	v_mov_b32_e32 v100, v0
	v_mov_b32_e32 v101, v0
	v_mov_b32_e32 v102, v0
	v_mov_b32_e32 v103, v0
	v_mov_b32_e32 v104, v0
	v_mov_b32_e32 v105, v0
	v_mov_b32_e32 v106, v0
	v_mov_b32_e32 v107, v0
	v_mov_b32_e32 v108, v0
	v_mov_b32_e32 v109, v0
	v_mov_b32_e32 v110, v0
	v_mov_b32_e32 v111, v0
	v_mov_b32_e32 v112, v0
	v_mov_b32_e32 v113, v0
	v_mov_b32_e32 v114, v0
	v_mov_b32_e32 v115, v0
	v_mov_b32_e32 v116, v0
	v_mov_b32_e32 v117, v0
	v_mov_b32_e32 v118, v0
	v_mov_b32_e32 v119, v0
	v_mov_b32_e32 v120, v0
	v_mov_b32_e32 v121, v0
	v_mov_b32_e32 v122, v0
	v_mov_b32_e32 v123, v0
	v_mov_b32_e32 v124, v0
	v_mov_b32_e32 v125, v0
	v_mov_b32_e32 v126, v0
	v_mov_b32_e32 v127, v0
	v_readlane_b32 s73, v250, 54
	v_readlane_b32 s74, v250, 55
	v_readlane_b32 s75, v250, 56
	v_readlane_b32 s76, v250, 57
	v_readlane_b32 s77, v250, 58
	v_readlane_b32 s78, v250, 59
	v_readlane_b32 s79, v250, 60
	v_readlane_b32 s80, v250, 61
	v_readlane_b32 s81, v250, 62
	v_readlane_b32 s82, v250, 63
	v_readlane_b32 s83, v249, 0
	v_readlane_b32 s86, v249, 3
	v_readlane_b32 s87, v249, 4
	s_waitcnt vmcnt(6)
	s_waitcnt lgkmcnt(0)
	v_readlane_b32 s44, v251, 5
	s_nop 0
	s_bitcmp1_b32 s44, 5
	s_cbranch_scc0 .Lnoprio_1
	s_setprio 2

.LBB0_75:
	s_and_b32 s4, s2, 7
	v_readlane_b32 s5, v251, 7
	s_or_b32 s11, s4, s5
	v_readlane_b32 s16, v250, 53
	s_lshr_b32 s10, s2, 3
	s_lshl_b32 s2, s11, 19
	v_readlane_b32 s22, v250, 59
	v_mov_b32_e32 v13, v200
	v_readlane_b32 s23, v250, 60
	s_add_u32 s4, s22, s2
	v_readlane_b32 s26, v250, 63
	v_ashrrev_i32_e32 v38, 2, v13
	v_lshlrev_b32_e32 v0, 3, v13
	s_addc_u32 s5, s23, 0
	s_lshl_b32 s2, s10, 18
	s_waitcnt vmcnt(0)
	v_and_b32_e32 v188, 24, v0
	v_add_u32_e32 v46, 0x80, v38
	v_readlane_b32 s27, v249, 0
	s_add_u32 s6, s26, s2
	v_lshlrev_b32_e32 v196, 1, v188
	v_add_u32_e32 v42, 64, v38
	v_ashrrev_i32_e32 v47, 31, v46
	v_add_u32_e32 v50, 0xc0, v38
	s_addc_u32 s7, s27, 0
	v_lshl_add_u64 v[176:177], s[4:5], 0, v[196:197]
	v_ashrrev_i32_e32 v39, 31, v38
	v_ashrrev_i32_e32 v43, 31, v42
	v_lshlrev_b64 v[4:5], 11, v[46:47]
	v_ashrrev_i32_e32 v51, 31, v50
	v_lshlrev_b64 v[0:1], 11, v[38:39]
	v_lshlrev_b64 v[2:3], 11, v[42:43]
	v_lshl_add_u64 v[48:49], v[176:177], 0, v[4:5]
	v_lshlrev_b64 v[4:5], 11, v[50:51]
	v_lshl_add_u64 v[178:179], s[6:7], 0, v[196:197]
	v_lshl_add_u64 v[40:41], v[176:177], 0, v[0:1]
	v_lshl_add_u64 v[44:45], v[176:177], 0, v[2:3]
	v_lshl_add_u64 v[52:53], v[176:177], 0, v[4:5]
	v_lshl_add_u64 v[54:55], v[178:179], 0, v[0:1]
	v_lshl_add_u64 v[56:57], v[178:179], 0, v[2:3]
	v_and_b32_e32 v192, 63, v200
	v_readfirstlane_b32 s44, v200
	v_lshrrev_b32_e32 v193, 2, v192
	v_and_b32_e32 v194, 3, v192
	v_lshrrev_b32_e32 v201, 4, v192
	s_lshr_b32 s44, s44, 6
	v_lshrrev_b32_e32 v212, 1, v201
	v_lshl_or_b32 v212, v212, 1, v212
	v_lshlrev_b32_e32 v201, 1, v201
	v_and_b32_e32 v201, 3, v201
	v_xor_b32_e32 v201, v201, v212
	v_xor_b32_e32 v206, v194, v201
	v_lshlrev_b32_e32 v206, 4, v206
	s_lshl_b32 s32, s44, 6
	v_add_u32_e32 v212, s32, v193
	v_lshlrev_b32_e32 v212, 11, v212
	v_add_u32_e32 v234, v212, v206
	v_add_u32_e32 v235, 0x8000, v234
	v_add_u32_e32 v236, 0x10000, v234
	v_add_u32_e32 v237, 0x18000, v234
	s_lshl_b32 s32, s44, 5
	v_add_u32_e32 v212, s32, v193
	v_lshlrev_b32_e32 v212, 11, v212
	v_add_u32_e32 v238, v212, v206
	v_add_u32_e32 v239, 0x8000, v238
	v_and_b32_e32 v193, 15, v192
	v_lshrrev_b32_e32 v194, 4, v192
	v_bfe_u32 v201, v192, 2, 2
	v_lshrrev_b32_e32 v212, 1, v201
	v_lshl_or_b32 v212, v212, 1, v212
	v_lshlrev_b32_e32 v201, 1, v201
	v_and_b32_e32 v201, 3, v201
	v_xor_b32_e32 v201, v201, v212
	v_xor_b32_e32 v206, v194, v201
	v_lshlrev_b32_e32 v206, 4, v206
	v_lshl_add_u32 v206, v193, 6, v206
	s_lshr_b32 s32, s44, 1
	s_lshl_b32 s32, s32, 13
	v_add_u32_e32 v240, s32, v206
	v_xor_b32_e32 v241, 32, v240
	s_and_b32 s32, s44, 1
	s_lshl_b32 s32, s32, 12
	s_add_u32 s32, s32, 0x4000
	v_add_u32_e32 v242, s32, v206
	v_xor_b32_e32 v243, 32, v242
	s_lshl_b32 s46, s44, 12
	s_lshl_b32 s47, s44, 11
	s_add_u32 s47, s47, 0x4000
	s_mov_b32 s40, s4
	s_mov_b32 s41, s5
	s_mov_b32 s42, s6
	s_mov_b32 s43, s7
	s_add_u32 m0, s46, 0x0
	s_nop 0
	global_load_lds_dwordx4 v234, s[40:41]
	s_add_u32 m0, m0, 0x400
	s_nop 0
	global_load_lds_dwordx4 v235, s[40:41]
	s_add_u32 m0, m0, 0x400
	s_nop 0
	global_load_lds_dwordx4 v236, s[40:41]
	s_add_u32 m0, m0, 0x400
	s_nop 0
	global_load_lds_dwordx4 v237, s[40:41]
	s_add_u32 m0, s47, 0x0
	s_nop 0
	global_load_lds_dwordx4 v238, s[42:43]
	s_add_u32 m0, m0, 0x400
	s_nop 0
	global_load_lds_dwordx4 v239, s[42:43]
	s_add_u32 s40, s40, 64
	s_addc_u32 s41, s41, 0
	s_add_u32 s42, s42, 64
	s_addc_u32 s43, s43, 0
	s_add_u32 m0, s46, 0x6000
	s_nop 0
	global_load_lds_dwordx4 v234, s[40:41]
	s_add_u32 m0, m0, 0x400
	s_nop 0
	global_load_lds_dwordx4 v235, s[40:41]
	s_add_u32 m0, m0, 0x400
	s_nop 0
	global_load_lds_dwordx4 v236, s[40:41]
	s_add_u32 m0, m0, 0x400
	s_nop 0
	global_load_lds_dwordx4 v237, s[40:41]
	s_add_u32 m0, s47, 0x6000
	s_nop 0
	global_load_lds_dwordx4 v238, s[42:43]
	s_add_u32 m0, m0, 0x400
	s_nop 0
	global_load_lds_dwordx4 v239, s[42:43]
	s_add_u32 s40, s40, 64
	s_addc_u32 s41, s41, 0
	s_add_u32 s42, s42, 64
	s_addc_u32 s43, s43, 0
	s_mov_b32 s45, 0xc000
	s_mov_b32 s49, 0
	v_and_b32_e32 v58, 0xfffff9f, v13
	v_lshrrev_b32_e32 v59, 1, v13
	v_and_b32_e32 v13, 0x5f, v13
	s_movk_i32 s2, 0x50
	v_and_b32_e32 v59, 16, v59
	v_mad_u32_u24 v13, v13, s2, 0
	v_mul_lo_u32 v60, v38, s2
	v_mul_lo_u32 v58, v58, s2
	v_add_u32_e32 v189, v13, v59
	v_add_u32_e32 v13, 0, v196
	v_readlane_b32 s17, v250, 54
	v_mov_b32_e32 v0, 0
	v_lshlrev_b64 v[38:39], 10, v[38:39]
	v_add_u32_e32 v58, 0, v58
	v_lshlrev_b64 v[42:43], 10, v[42:43]
	v_lshlrev_b64 v[46:47], 10, v[46:47]
	v_lshlrev_b64 v[50:51], 10, v[50:51]
	v_add_u32_e32 v191, v13, v60
	s_mov_b32 s16, 64
	s_mov_b32 s17, 0
	v_mov_b32_e32 v1, v0
	v_mov_b32_e32 v2, v0
	v_mov_b32_e32 v3, v0
	v_mov_b32_e32 v4, v0
	v_mov_b32_e32 v5, v0
	v_mov_b32_e32 v6, v0
	v_mov_b32_e32 v7, v0
	v_mov_b32_e32 v8, v0
	v_mov_b32_e32 v9, v0
	v_mov_b32_e32 v10, v0
	v_mov_b32_e32 v11, v0
	v_mov_b32_e32 v12, v0
	v_lshlrev_b64 v[180:181], 1, v[38:39]
	v_add_u32_e32 v190, v58, v59
	v_lshlrev_b64 v[182:183], 1, v[42:43]
	v_lshlrev_b64 v[184:185], 1, v[46:47]
	v_lshlrev_b64 v[186:187], 1, v[50:51]
	v_mov_b32_e32 v13, v0
	v_mov_b32_e32 v38, v0
	v_mov_b32_e32 v39, v0
	v_mov_b32_e32 v14, v0
	v_mov_b32_e32 v15, v0
	v_mov_b32_e32 v16, v0
	v_mov_b32_e32 v17, v0
	v_mov_b32_e32 v18, v0
	v_mov_b32_e32 v19, v0
	v_mov_b32_e32 v20, v0
	v_mov_b32_e32 v21, v0
	v_mov_b32_e32 v22, v0
	v_mov_b32_e32 v23, v0
	v_mov_b32_e32 v24, v0
	v_mov_b32_e32 v25, v0
	v_mov_b32_e32 v26, v0
	v_mov_b32_e32 v27, v0
	v_mov_b32_e32 v28, v0
	v_mov_b32_e32 v29, v0
	v_mov_b32_e32 v30, v0
	v_mov_b32_e32 v31, v0
	v_mov_b32_e32 v32, v0
	v_mov_b32_e32 v33, v0
	v_mov_b32_e32 v34, v0
	v_mov_b32_e32 v35, v0
	v_mov_b32_e32 v36, v0
	v_mov_b32_e32 v37, v0
	v_mov_b32_e32 v40, v0
	v_mov_b32_e32 v41, v0
	v_mov_b32_e32 v42, v0
	v_mov_b32_e32 v43, v0
	v_mov_b32_e32 v44, v0
	v_mov_b32_e32 v45, v0
	v_mov_b32_e32 v46, v0
	v_mov_b32_e32 v47, v0
	v_mov_b32_e32 v48, v0
	v_mov_b32_e32 v49, v0
	v_mov_b32_e32 v50, v0
	v_mov_b32_e32 v51, v0
	v_mov_b32_e32 v52, v0
	v_mov_b32_e32 v53, v0
	v_mov_b32_e32 v54, v0
	v_mov_b32_e32 v55, v0
	v_mov_b32_e32 v56, v0
	v_mov_b32_e32 v57, v0
	v_mov_b32_e32 v58, v0
	v_mov_b32_e32 v59, v0
	v_mov_b32_e32 v60, v0
	v_mov_b32_e32 v61, v0
	v_mov_b32_e32 v62, v0
	v_mov_b32_e32 v63, v0
	v_mov_b32_e32 v64, v0
	v_mov_b32_e32 v65, v0
	v_mov_b32_e32 v66, v0
	v_mov_b32_e32 v67, v0
	v_mov_b32_e32 v68, v0
	v_mov_b32_e32 v69, v0
	v_mov_b32_e32 v70, v0
	v_mov_b32_e32 v71, v0
	v_mov_b32_e32 v72, v0
	v_mov_b32_e32 v73, v0
	v_mov_b32_e32 v74, v0
	v_mov_b32_e32 v75, v0
	v_mov_b32_e32 v76, v0
	v_mov_b32_e32 v77, v0
	v_mov_b32_e32 v78, v0
	v_mov_b32_e32 v79, v0
	v_mov_b32_e32 v80, v0
	v_mov_b32_e32 v81, v0
	v_mov_b32_e32 v82, v0
	v_mov_b32_e32 v83, v0
	v_mov_b32_e32 v84, v0
	v_mov_b32_e32 v85, v0
	v_mov_b32_e32 v86, v0
	v_mov_b32_e32 v87, v0
	v_mov_b32_e32 v88, v0
	v_mov_b32_e32 v89, v0
	v_mov_b32_e32 v90, v0
	v_mov_b32_e32 v91, v0
	v_mov_b32_e32 v92, v0
	v_mov_b32_e32 v93, v0
	v_mov_b32_e32 v94, v0
	v_mov_b32_e32 v95, v0
	v_mov_b32_e32 v96, v0
	v_mov_b32_e32 v97, v0
	v_mov_b32_e32 v98, v0
	v_mov_b32_e32 v99, v0
	v_mov_b32_e32 v100, v0
	v_mov_b32_e32 v101, v0
	v_mov_b32_e32 v102, v0
	v_mov_b32_e32 v103, v0
	v_mov_b32_e32 v104, v0
	v_mov_b32_e32 v105, v0
	v_mov_b32_e32 v106, v0
	v_mov_b32_e32 v107, v0
	v_mov_b32_e32 v108, v0
	v_mov_b32_e32 v109, v0
	v_mov_b32_e32 v110, v0
	v_mov_b32_e32 v111, v0
	v_mov_b32_e32 v112, v0
	v_mov_b32_e32 v113, v0
	v_mov_b32_e32 v114, v0
	v_mov_b32_e32 v115, v0
	v_mov_b32_e32 v116, v0
	v_mov_b32_e32 v117, v0
	v_mov_b32_e32 v118, v0
	v_mov_b32_e32 v119, v0
	v_mov_b32_e32 v120, v0
	v_mov_b32_e32 v121, v0
	v_mov_b32_e32 v122, v0
	v_mov_b32_e32 v123, v0
	v_mov_b32_e32 v124, v0
	v_mov_b32_e32 v125, v0
	v_mov_b32_e32 v126, v0
	v_mov_b32_e32 v127, v0
	v_readlane_b32 s18, v250, 55
	v_readlane_b32 s19, v250, 56
	v_readlane_b32 s20, v250, 57
	v_readlane_b32 s21, v250, 58
	v_readlane_b32 s24, v250, 61
	v_readlane_b32 s25, v250, 62
	v_readlane_b32 s28, v249, 1
	v_readlane_b32 s29, v249, 2
	v_readlane_b32 s30, v249, 3
	v_readlane_b32 s31, v249, 4
	s_waitcnt vmcnt(6)
	s_waitcnt lgkmcnt(0)
	v_readlane_b32 s44, v251, 5
	s_nop 0
	s_bitcmp1_b32 s44, 5
	s_cbranch_scc0 .Lnoprio_0
	s_setprio 2

.LBB0_106:
	s_and_b32 s2, s2, 7
	v_readlane_b32 s4, v251, 7
	s_or_b32 s16, s2, s4
	s_lshl_b32 s4, s15, 7
	s_lshl_b32 s14, s16, 19
	v_mov_b32_e32 v56, v200
	s_add_u32 s6, s20, s14
	s_mov_b32 s5, s3
	s_addc_u32 s7, s21, 0
	v_ashrrev_i32_e32 v36, 2, v56
	v_lshlrev_b32_e32 v0, 3, v56
	s_lshl_b64 s[8:9], s[4:5], 11
	v_readlane_b32 s10, v249, 19
	s_waitcnt vmcnt(0)
	v_and_b32_e32 v188, 24, v0
	v_add_u32_e32 v44, 0x80, v36
	v_readlane_b32 s11, v249, 20
	s_add_u32 s8, s10, s8
	v_lshlrev_b32_e32 v196, 1, v188
	v_add_u32_e32 v40, 64, v36
	v_ashrrev_i32_e32 v45, 31, v44
	v_add_u32_e32 v48, 0xc0, v36
	s_addc_u32 s9, s11, s9
	v_lshl_add_u64 v[176:177], s[6:7], 0, v[196:197]
	v_ashrrev_i32_e32 v37, 31, v36
	v_ashrrev_i32_e32 v41, 31, v40
	v_lshlrev_b64 v[4:5], 11, v[44:45]
	v_ashrrev_i32_e32 v49, 31, v48
	v_lshlrev_b64 v[0:1], 11, v[36:37]
	v_lshlrev_b64 v[2:3], 11, v[40:41]
	v_lshl_add_u64 v[46:47], v[176:177], 0, v[4:5]
	v_lshlrev_b64 v[4:5], 11, v[48:49]
	v_lshl_add_u64 v[178:179], s[8:9], 0, v[196:197]
	v_lshl_add_u64 v[38:39], v[176:177], 0, v[0:1]
	v_lshl_add_u64 v[42:43], v[176:177], 0, v[2:3]
	v_lshl_add_u64 v[50:51], v[176:177], 0, v[4:5]
	v_lshl_add_u64 v[52:53], v[178:179], 0, v[0:1]
	v_lshl_add_u64 v[54:55], v[178:179], 0, v[2:3]
	v_and_b32_e32 v192, 63, v200
	v_readfirstlane_b32 s44, v200
	v_lshrrev_b32_e32 v193, 2, v192
	v_and_b32_e32 v194, 3, v192
	v_lshrrev_b32_e32 v201, 4, v192
	s_lshr_b32 s44, s44, 6
	v_lshrrev_b32_e32 v212, 1, v201
	v_lshl_or_b32 v212, v212, 1, v212
	v_lshlrev_b32_e32 v201, 1, v201
	v_and_b32_e32 v201, 3, v201
	v_xor_b32_e32 v201, v201, v212
	v_xor_b32_e32 v206, v194, v201
	v_lshlrev_b32_e32 v206, 4, v206
	s_lshl_b32 s32, s44, 6
	v_add_u32_e32 v212, s32, v193
	v_lshlrev_b32_e32 v212, 11, v212
	v_add_u32_e32 v234, v212, v206
	v_add_u32_e32 v235, 0x8000, v234
	v_add_u32_e32 v236, 0x10000, v234
	v_add_u32_e32 v237, 0x18000, v234
	s_lshl_b32 s32, s44, 5
	v_add_u32_e32 v212, s32, v193
	v_lshlrev_b32_e32 v212, 11, v212
	v_add_u32_e32 v238, v212, v206
	v_add_u32_e32 v239, 0x8000, v238
	v_and_b32_e32 v193, 15, v192
	v_lshrrev_b32_e32 v194, 4, v192
	v_bfe_u32 v201, v192, 2, 2
	v_lshrrev_b32_e32 v212, 1, v201
	v_lshl_or_b32 v212, v212, 1, v212
	v_lshlrev_b32_e32 v201, 1, v201
	v_and_b32_e32 v201, 3, v201
	v_xor_b32_e32 v201, v201, v212
	v_xor_b32_e32 v206, v194, v201
	v_lshlrev_b32_e32 v206, 4, v206
	v_lshl_add_u32 v206, v193, 6, v206
	s_lshr_b32 s32, s44, 1
	s_lshl_b32 s32, s32, 13
	v_add_u32_e32 v240, s32, v206
	v_xor_b32_e32 v241, 32, v240
	s_and_b32 s32, s44, 1
	s_lshl_b32 s32, s32, 12
	s_add_u32 s32, s32, 0x4000
	v_add_u32_e32 v242, s32, v206
	v_xor_b32_e32 v243, 32, v242
	s_lshl_b32 s46, s44, 12
	s_lshl_b32 s47, s44, 11
	s_add_u32 s47, s47, 0x4000
	s_mov_b32 s40, s6
	s_mov_b32 s41, s7
	s_mov_b32 s42, s8
	s_mov_b32 s43, s9
	s_add_u32 m0, s46, 0x0
	s_nop 0
	global_load_lds_dwordx4 v234, s[40:41]
	s_add_u32 m0, m0, 0x400
	s_nop 0
	global_load_lds_dwordx4 v235, s[40:41]
	s_add_u32 m0, m0, 0x400
	s_nop 0
	global_load_lds_dwordx4 v236, s[40:41]
	s_add_u32 m0, m0, 0x400
	s_nop 0
	global_load_lds_dwordx4 v237, s[40:41]
	s_add_u32 m0, s47, 0x0
	s_nop 0
	global_load_lds_dwordx4 v238, s[42:43]
	s_add_u32 m0, m0, 0x400
	s_nop 0
	global_load_lds_dwordx4 v239, s[42:43]
	s_add_u32 s40, s40, 64
	s_addc_u32 s41, s41, 0
	s_add_u32 s42, s42, 64
	s_addc_u32 s43, s43, 0
	s_add_u32 m0, s46, 0x6000
	s_nop 0
	global_load_lds_dwordx4 v234, s[40:41]
	s_add_u32 m0, m0, 0x400
	s_nop 0
	global_load_lds_dwordx4 v235, s[40:41]
	s_add_u32 m0, m0, 0x400
	s_nop 0
	global_load_lds_dwordx4 v236, s[40:41]
	s_add_u32 m0, m0, 0x400
	s_nop 0
	global_load_lds_dwordx4 v237, s[40:41]
	s_add_u32 m0, s47, 0x6000
	s_nop 0
	global_load_lds_dwordx4 v238, s[42:43]
	s_add_u32 m0, m0, 0x400
	s_nop 0
	global_load_lds_dwordx4 v239, s[42:43]
	s_add_u32 s40, s40, 64
	s_addc_u32 s41, s41, 0
	s_add_u32 s42, s42, 64
	s_addc_u32 s43, s43, 0
	s_mov_b32 s45, 0xc000
	s_mov_b32 s49, 0
	v_and_b32_e32 v57, 0xfffff9f, v56
	v_lshrrev_b32_e32 v58, 1, v56
	v_and_b32_e32 v56, 0x5f, v56
	s_movk_i32 s2, 0x50
	v_and_b32_e32 v58, 16, v58
	v_mad_u32_u24 v56, v56, s2, 0
	v_mul_lo_u32 v59, v36, s2
	v_mul_lo_u32 v57, v57, s2
	v_add_u32_e32 v189, v56, v58
	v_add_u32_e32 v56, 0, v196
	v_mov_b32_e32 v0, 0
	v_lshlrev_b64 v[36:37], 10, v[36:37]
	v_add_u32_e32 v57, 0, v57
	v_lshlrev_b64 v[40:41], 10, v[40:41]
	v_lshlrev_b64 v[44:45], 10, v[44:45]
	v_lshlrev_b64 v[48:49], 10, v[48:49]
	v_add_u32_e32 v191, v56, v59
	s_mov_b32 s5, 64
	s_mov_b32 s17, 0
	v_mov_b32_e32 v1, v0
	v_mov_b32_e32 v2, v0
	v_mov_b32_e32 v3, v0
	v_mov_b32_e32 v4, v0
	v_mov_b32_e32 v5, v0
	v_mov_b32_e32 v6, v0
	v_mov_b32_e32 v7, v0
	v_mov_b32_e32 v8, v0
	v_mov_b32_e32 v9, v0
	v_mov_b32_e32 v10, v0
	v_mov_b32_e32 v11, v0
	v_lshlrev_b64 v[180:181], 1, v[36:37]
	v_add_u32_e32 v190, v57, v58
	v_lshlrev_b64 v[182:183], 1, v[40:41]
	v_lshlrev_b64 v[184:185], 1, v[44:45]
	v_lshlrev_b64 v[186:187], 1, v[48:49]
	v_mov_b32_e32 v36, v0
	v_mov_b32_e32 v37, v0
	v_mov_b32_e32 v38, v0
	v_mov_b32_e32 v39, v0
	v_mov_b32_e32 v40, v0
	v_mov_b32_e32 v41, v0
	v_mov_b32_e32 v42, v0
	v_mov_b32_e32 v12, v0
	v_mov_b32_e32 v13, v0
	v_mov_b32_e32 v14, v0
	v_mov_b32_e32 v15, v0
	v_mov_b32_e32 v16, v0
	v_mov_b32_e32 v17, v0
	v_mov_b32_e32 v18, v0
	v_mov_b32_e32 v19, v0
	v_mov_b32_e32 v20, v0
	v_mov_b32_e32 v21, v0
	v_mov_b32_e32 v22, v0
	v_mov_b32_e32 v23, v0
	v_mov_b32_e32 v24, v0
	v_mov_b32_e32 v25, v0
	v_mov_b32_e32 v26, v0
	v_mov_b32_e32 v27, v0
	v_mov_b32_e32 v28, v0
	v_mov_b32_e32 v29, v0
	v_mov_b32_e32 v30, v0
	v_mov_b32_e32 v31, v0
	v_mov_b32_e32 v32, v0
	v_mov_b32_e32 v33, v0
	v_mov_b32_e32 v34, v0
	v_mov_b32_e32 v35, v0
	v_mov_b32_e32 v43, v0
	v_mov_b32_e32 v44, v0
	v_mov_b32_e32 v45, v0
	v_mov_b32_e32 v46, v0
	v_mov_b32_e32 v47, v0
	v_mov_b32_e32 v48, v0
	v_mov_b32_e32 v49, v0
	v_mov_b32_e32 v50, v0
	v_mov_b32_e32 v51, v0
	v_mov_b32_e32 v52, v0
	v_mov_b32_e32 v53, v0
	v_mov_b32_e32 v54, v0
	v_mov_b32_e32 v55, v0
	v_mov_b32_e32 v56, v0
	v_mov_b32_e32 v57, v0
	v_mov_b32_e32 v58, v0
	v_mov_b32_e32 v59, v0
	v_mov_b32_e32 v60, v0
	v_mov_b32_e32 v61, v0
	v_mov_b32_e32 v62, v0
	v_mov_b32_e32 v63, v0
	v_mov_b32_e32 v64, v0
	v_mov_b32_e32 v65, v0
	v_mov_b32_e32 v66, v0
	v_mov_b32_e32 v67, v0
	v_mov_b32_e32 v68, v0
	v_mov_b32_e32 v69, v0
	v_mov_b32_e32 v70, v0
	v_mov_b32_e32 v71, v0
	v_mov_b32_e32 v72, v0
	v_mov_b32_e32 v73, v0
	v_mov_b32_e32 v74, v0
	v_mov_b32_e32 v75, v0
	v_mov_b32_e32 v76, v0
	v_mov_b32_e32 v77, v0
	v_mov_b32_e32 v78, v0
	v_mov_b32_e32 v79, v0
	v_mov_b32_e32 v80, v0
	v_mov_b32_e32 v81, v0
	v_mov_b32_e32 v82, v0
	v_mov_b32_e32 v83, v0
	v_mov_b32_e32 v84, v0
	v_mov_b32_e32 v85, v0
	v_mov_b32_e32 v86, v0
	v_mov_b32_e32 v87, v0
	v_mov_b32_e32 v88, v0
	v_mov_b32_e32 v89, v0
	v_mov_b32_e32 v90, v0
	v_mov_b32_e32 v91, v0
	v_mov_b32_e32 v92, v0
	v_mov_b32_e32 v93, v0
	v_mov_b32_e32 v94, v0
	v_mov_b32_e32 v95, v0
	v_mov_b32_e32 v96, v0
	v_mov_b32_e32 v97, v0
	v_mov_b32_e32 v98, v0
	v_mov_b32_e32 v99, v0
	v_mov_b32_e32 v100, v0
	v_mov_b32_e32 v101, v0
	v_mov_b32_e32 v102, v0
	v_mov_b32_e32 v103, v0
	v_mov_b32_e32 v104, v0
	v_mov_b32_e32 v105, v0
	v_mov_b32_e32 v106, v0
	v_mov_b32_e32 v107, v0
	v_mov_b32_e32 v108, v0
	v_mov_b32_e32 v109, v0
	v_mov_b32_e32 v110, v0
	v_mov_b32_e32 v111, v0
	v_mov_b32_e32 v112, v0
	v_mov_b32_e32 v113, v0
	v_mov_b32_e32 v114, v0
	v_mov_b32_e32 v115, v0
	v_mov_b32_e32 v116, v0
	v_mov_b32_e32 v117, v0
	v_mov_b32_e32 v118, v0
	v_mov_b32_e32 v119, v0
	v_mov_b32_e32 v120, v0
	v_mov_b32_e32 v121, v0
	v_mov_b32_e32 v122, v0
	v_mov_b32_e32 v123, v0
	v_mov_b32_e32 v124, v0
	v_mov_b32_e32 v125, v0
	v_mov_b32_e32 v126, v0
	v_mov_b32_e32 v127, v0
	s_waitcnt vmcnt(6)
	s_waitcnt lgkmcnt(0)
	v_readlane_b32 s44, v251, 5
	s_nop 0
	s_bitcmp1_b32 s44, 5
	s_cbranch_scc0 .Lnoprio_2
	s_setprio 2
